# kernel end: dropped the final s_waitcnt vmcnt(0) + s_barrier before s_endpgm (stores complete on their own)
# baseline (speedup 1.0000x reference)
; #define PG8_WAIT_V(n) asm volatile("s_waitcnt vmcnt(" #n ")" ::: "memory")
; #define PG8_BAR __builtin_amdgcn_s_barrier()
; template <class Epi, class Sched, bool ALIGN_EPI = false, bool SP2 = false>
; __device__ __forceinline__ void gemm_phase(PG8_LAS unsigned char* lds, const Gemm g, const Sched& S, const Epi& E) {
;     ...
;     PG8_WAIT_V(0);
;     if constexpr (!ALIGN_EPI) { if (wr == 0) PG8_BAR; }
;     PG8_BAR;
.LBB0_1043:
.LBB0_1044:
	s_endpgm
